# v20 + removed per-segment s_setprio toggles in GEMM main loop; followers poll cross-XCC generation directly
# speedup vs baseline: 1.0290x; 1.0054x over previous
; #define LDA(dst, b, h) _Pragma("unroll") for (int m = 0; m < 4; ++m) _Pragma("unroll") for (int k = 0; k < 2; ++k) \
;     dst[m][k] = *reinterpret_cast<const bf16x8*>((char*)SA(b, h) + lds_byte(wr * 64 + m * 16 + fr, k * 32 + fq * 8))
; #define LDB(dst, b, h) _Pragma("unroll") for (int n = 0; n < 2; ++n) _Pragma("unroll") for (int k = 0; k < 2; ++k) \
;     dst[n][k] = *reinterpret_cast<const bf16x8*>((char*)SB(b, h) + lds_byte(wc * 32 + n * 16 + fr, k * 32 + fq * 8))
; #define MMA(ai, bj, At_, Bt_) do { __builtin_amdgcn_s_setprio(1); \
;     _Pragma("unroll") for (int m = 0; m < 4; ++m) _Pragma("unroll") for (int n = 0; n < 2; ++n) _Pragma("unroll") for (int k = 0; k < 2; ++k) \
;       acc[ai][bj][m][n] = __builtin_amdgcn_mfma_f32_16x16x32_bf16(Bt_[n][k], At_[m][k], acc[ai][bj][m][n], 0, 0, 0); \
;     __builtin_amdgcn_s_setprio(0); } while (0)
; #define WAIT_L(n) asm volatile("s_waitcnt lgkmcnt(" #n ")" ::: "memory")
; #define BAR __builtin_amdgcn_s_barrier()
; #define SCHED __builtin_amdgcn_sched_barrier(0)
; __device__ __forceinline__ void gemm_tile(const TileDesc& td, unsigned char* lds) {
;     ...
;     for (int t = 0; t < nt - 2; t += 2) {
;         LDB(B0, 0, 0); SCHED; LDA(At, 0, 0); STAGE(SA(1, 1), A, lda, brow + HALF, t + 1);
;         WAIT_L(8); BAR; WAIT_L(0); MMA(0, 0, At, B0); BAR; SCHED;
;         LDB(B1, 0, 1); STAGE(SB(0, 0), Bt, ldb, bcol, t + 2);
;         BAR; WAIT_L(0); MMA(0, 1, At, B1); BAR;
;         LDA(At, 0, 1); STAGE(SA(0, 0), A, lda, brow, t + 2);
;         BAR; WAIT_L(0); MMA(1, 0, At, B0); BAR; SCHED;
.LBB0_247:
	ds_read_b128 v[190:193], v183
	ds_read_b128 v[194:197], v183 offset:1024
	ds_read_b128 v[198:201], v183 offset:2048
	ds_read_b128 v[202:205], v183 offset:3072
	s_add_u32 s7, s4, s78
	s_addc_u32 s62, s5, s79
	s_add_u32 s30, s7, 0x80
	v_add_u32_e32 v162, 0xc000, v139
	s_addc_u32 s31, s62, 0
	v_readfirstlane_b32 s63, v162
	v_add_u32_e32 v252, v182, v154
	v_lshl_add_u64 v[160:161], s[30:31], 0, v[128:129]
	s_mov_b32 m0, s63
	v_add_u32_e32 v162, 0xe000, v139
	ds_read_b128 v[206:209], v252
	ds_read_b128 v[210:213], v252 offset:1024
	ds_read_b128 v[214:217], v184
	ds_read_b128 v[218:221], v184 offset:1024
	ds_read_b128 v[222:225], v185
	ds_read_b128 v[226:229], v185 offset:1024
	ds_read_b128 v[230:233], v186
	ds_read_b128 v[234:237], v186 offset:1024
	global_load_lds_dwordx4 v[160:161], off
	v_lshl_add_u64 v[160:161], s[30:31], 0, v[130:131]
	v_readfirstlane_b32 s30, v162
	s_mov_b32 m0, s30
	s_nop 0
	global_load_lds_dwordx4 v[160:161], off
	s_waitcnt lgkmcnt(8)
	s_barrier
	s_waitcnt lgkmcnt(0)
	s_waitcnt lgkmcnt(0)
	v_mfma_f32_16x16x32_bf16 v[100:103], v[190:193], v[206:209], v[100:103]
	v_mfma_f32_16x16x32_bf16 v[124:127], v[198:201], v[206:209], v[124:127]
	v_mfma_f32_16x16x32_bf16 v[120:123], v[190:193], v[214:217], v[120:123]
	v_mfma_f32_16x16x32_bf16 v[116:119], v[198:201], v[214:217], v[116:119]
	v_mfma_f32_16x16x32_bf16 v[112:115], v[190:193], v[222:225], v[112:115]
	v_mfma_f32_16x16x32_bf16 v[108:111], v[198:201], v[222:225], v[108:111]
	v_mfma_f32_16x16x32_bf16 v[104:107], v[190:193], v[230:233], v[104:107]
	v_mfma_f32_16x16x32_bf16 v[96:99], v[198:201], v[230:233], v[96:99]
	v_mfma_f32_16x16x32_bf16 v[100:103], v[194:197], v[210:213], v[100:103]
	v_mfma_f32_16x16x32_bf16 v[124:127], v[202:205], v[210:213], v[124:127]
	v_mfma_f32_16x16x32_bf16 v[120:123], v[194:197], v[218:221], v[120:123]
	v_mfma_f32_16x16x32_bf16 v[116:119], v[202:205], v[218:221], v[116:119]
	v_mfma_f32_16x16x32_bf16 v[112:115], v[194:197], v[226:229], v[112:115]
	v_mfma_f32_16x16x32_bf16 v[108:111], v[202:205], v[226:229], v[108:111]
	v_mfma_f32_16x16x32_bf16 v[104:107], v[194:197], v[234:237], v[104:107]
	v_mfma_f32_16x16x32_bf16 v[96:99], v[202:205], v[234:237], v[96:99]
	s_barrier
	s_add_i32 s3, s3, 2
	s_add_u32 s63, s18, s78
	s_addc_u32 s65, s19, s79
	s_add_u32 s30, s63, 0x100
	s_addc_u32 s31, s65, 0
	v_readfirstlane_b32 s66, v152
	v_lshl_add_u64 v[168:169], s[30:31], 0, v[132:133]
	s_mov_b32 m0, s66
	ds_read_b128 v[238:241], v187
	ds_read_b128 v[242:245], v187 offset:1024
	ds_read_b128 v[246:249], v187 offset:2048
	ds_read_b128 v[160:163], v187 offset:3072
	global_load_lds_dwordx4 v[168:169], off
	v_lshl_add_u64 v[168:169], s[30:31], 0, v[136:137]
	v_readfirstlane_b32 s30, v153
	s_mov_b32 m0, s30
	s_nop 0
	global_load_lds_dwordx4 v[168:169], off
	s_barrier
	s_waitcnt lgkmcnt(0)
	s_waitcnt lgkmcnt(0)
	v_mfma_f32_16x16x32_bf16 v[92:95], v[238:241], v[206:209], v[92:95]
	v_mfma_f32_16x16x32_bf16 v[88:91], v[246:249], v[206:209], v[88:91]
	v_mfma_f32_16x16x32_bf16 v[84:87], v[238:241], v[214:217], v[84:87]
	v_mfma_f32_16x16x32_bf16 v[80:83], v[246:249], v[214:217], v[80:83]
	v_mfma_f32_16x16x32_bf16 v[76:79], v[238:241], v[222:225], v[76:79]
	v_mfma_f32_16x16x32_bf16 v[72:75], v[246:249], v[222:225], v[72:75]
	v_mfma_f32_16x16x32_bf16 v[68:71], v[238:241], v[230:233], v[68:71]
	v_mfma_f32_16x16x32_bf16 v[64:67], v[246:249], v[230:233], v[64:67]
	v_mfma_f32_16x16x32_bf16 v[92:95], v[242:245], v[210:213], v[92:95]
	v_mfma_f32_16x16x32_bf16 v[88:91], v[160:163], v[210:213], v[88:91]
	v_mfma_f32_16x16x32_bf16 v[84:87], v[242:245], v[218:221], v[84:87]
	v_mfma_f32_16x16x32_bf16 v[80:83], v[160:163], v[218:221], v[80:83]
	v_mfma_f32_16x16x32_bf16 v[76:79], v[242:245], v[226:229], v[76:79]
	v_mfma_f32_16x16x32_bf16 v[72:75], v[160:163], v[226:229], v[72:75]
	v_mfma_f32_16x16x32_bf16 v[68:71], v[242:245], v[234:237], v[68:71]
	v_mfma_f32_16x16x32_bf16 v[64:67], v[160:163], v[234:237], v[64:67]
	s_add_u32 s66, s24, s78
	s_addc_u32 s67, s25, s79
	s_add_u32 s30, s66, 0x100
	s_addc_u32 s31, s67, 0
	v_readfirstlane_b32 s70, v139
	v_lshl_add_u64 v[168:169], s[30:31], 0, v[128:129]
	s_mov_b32 m0, s70
	s_barrier
	ds_read_b128 v[206:209], v252 offset:16384
	ds_read_b128 v[210:213], v252 offset:17408
	ds_read_b128 v[214:217], v184 offset:16384
	ds_read_b128 v[218:221], v184 offset:17408
	ds_read_b128 v[222:225], v185 offset:16384
	ds_read_b128 v[226:229], v185 offset:17408
	ds_read_b128 v[230:233], v186 offset:16384
	ds_read_b128 v[234:237], v186 offset:17408
	global_load_lds_dwordx4 v[168:169], off
	v_lshl_add_u64 v[168:169], s[30:31], 0, v[130:131]
	v_readfirstlane_b32 s30, v155
	s_mov_b32 m0, s30
	s_nop 0
	global_load_lds_dwordx4 v[168:169], off
	s_barrier
	s_waitcnt lgkmcnt(0)
	s_waitcnt lgkmcnt(0)
	v_mfma_f32_16x16x32_bf16 v[60:63], v[190:193], v[206:209], v[60:63]
	v_mfma_f32_16x16x32_bf16 v[56:59], v[198:201], v[206:209], v[56:59]
	v_mfma_f32_16x16x32_bf16 v[52:55], v[190:193], v[214:217], v[52:55]
	v_mfma_f32_16x16x32_bf16 v[48:51], v[198:201], v[214:217], v[48:51]
	v_mfma_f32_16x16x32_bf16 v[44:47], v[190:193], v[222:225], v[44:47]
	v_mfma_f32_16x16x32_bf16 v[40:43], v[198:201], v[222:225], v[40:43]
	v_mfma_f32_16x16x32_bf16 v[36:39], v[190:193], v[230:233], v[36:39]
	v_mfma_f32_16x16x32_bf16 v[32:35], v[198:201], v[230:233], v[32:35]
	v_mfma_f32_16x16x32_bf16 v[60:63], v[194:197], v[210:213], v[60:63]
	v_mfma_f32_16x16x32_bf16 v[56:59], v[202:205], v[210:213], v[56:59]
	v_mfma_f32_16x16x32_bf16 v[52:55], v[194:197], v[218:221], v[52:55]
	v_mfma_f32_16x16x32_bf16 v[48:51], v[202:205], v[218:221], v[48:51]
	v_mfma_f32_16x16x32_bf16 v[44:47], v[194:197], v[226:229], v[44:47]
	v_mfma_f32_16x16x32_bf16 v[40:43], v[202:205], v[226:229], v[40:43]
	v_mfma_f32_16x16x32_bf16 v[36:39], v[194:197], v[234:237], v[36:39]
	v_mfma_f32_16x16x32_bf16 v[32:35], v[202:205], v[234:237], v[32:35]
	s_barrier
; #define LDA(dst, b, h) _Pragma("unroll") for (int m = 0; m < 4; ++m) _Pragma("unroll") for (int k = 0; k < 2; ++k) \
;     dst[m][k] = *reinterpret_cast<const bf16x8*>((char*)SA(b, h) + lds_byte(wr * 64 + m * 16 + fr, k * 32 + fq * 8))
; #define LDB(dst, b, h) _Pragma("unroll") for (int n = 0; n < 2; ++n) _Pragma("unroll") for (int k = 0; k < 2; ++k) \
;     dst[n][k] = *reinterpret_cast<const bf16x8*>((char*)SB(b, h) + lds_byte(wc * 32 + n * 16 + fr, k * 32 + fq * 8))
; #define MMA(ai, bj, At_, Bt_) do { __builtin_amdgcn_s_setprio(1); \
;     _Pragma("unroll") for (int m = 0; m < 4; ++m) _Pragma("unroll") for (int n = 0; n < 2; ++n) _Pragma("unroll") for (int k = 0; k < 2; ++k) \
;       acc[ai][bj][m][n] = __builtin_amdgcn_mfma_f32_16x16x32_bf16(Bt_[n][k], At_[m][k], acc[ai][bj][m][n], 0, 0, 0); \
;     __builtin_amdgcn_s_setprio(0); } while (0)
; #define WAIT_V(n) asm volatile("s_waitcnt vmcnt(" #n ")" ::: "memory")
; #define WAIT_L(n) asm volatile("s_waitcnt lgkmcnt(" #n ")" ::: "memory")
; #define BAR __builtin_amdgcn_s_barrier()
; #define SCHED __builtin_amdgcn_sched_barrier(0)
; __device__ __forceinline__ void gemm_tile(const TileDesc& td, unsigned char* lds) {
;     ...
;         STAGE(SB(0, 1), Bt, ldb, bcol + HALF, t + 2);
;         WAIT_V(6); BAR; MMA(1, 1, At, B1); BAR;
;         LDB(B0, 1, 0); SCHED; LDA(At, 1, 0); STAGE(SA(0, 1), A, lda, brow + HALF, t + 2);
;         WAIT_L(8); BAR; WAIT_L(0); MMA(0, 0, At, B0); BAR; SCHED;
;         LDB(B1, 1, 1); STAGE(SB(1, 0), Bt, ldb, bcol, t + 3);
;         BAR; WAIT_L(0); MMA(0, 1, At, B1); BAR;
;         LDA(At, 1, 1); STAGE(SA(1, 0), A, lda, brow, t + 3);
	s_add_u32 s70, s80, s78
	s_addc_u32 s88, s81, s79
	s_add_u32 s30, s70, 0x100
	s_addc_u32 s31, s88, 0
	v_readfirstlane_b32 s89, v156
	v_lshl_add_u64 v[168:169], s[30:31], 0, v[132:133]
	s_mov_b32 m0, s89
	s_nop 0
	global_load_lds_dwordx4 v[168:169], off
	v_lshl_add_u64 v[168:169], s[30:31], 0, v[136:137]
	v_readfirstlane_b32 s30, v157
	s_mov_b32 m0, s30
	s_nop 0
	global_load_lds_dwordx4 v[168:169], off
	s_waitcnt vmcnt(6)
	s_barrier
	v_mfma_f32_16x16x32_bf16 v[28:31], v[238:241], v[206:209], v[28:31]
	v_mfma_f32_16x16x32_bf16 v[24:27], v[246:249], v[206:209], v[24:27]
	v_mfma_f32_16x16x32_bf16 v[20:23], v[238:241], v[214:217], v[20:23]
	v_mfma_f32_16x16x32_bf16 v[16:19], v[246:249], v[214:217], v[16:19]
	v_mfma_f32_16x16x32_bf16 v[12:15], v[238:241], v[222:225], v[12:15]
	v_mfma_f32_16x16x32_bf16 v[8:11], v[246:249], v[222:225], v[8:11]
	v_mfma_f32_16x16x32_bf16 v[4:7], v[238:241], v[230:233], v[4:7]
	v_mfma_f32_16x16x32_bf16 v[0:3], v[246:249], v[230:233], v[0:3]
	v_mfma_f32_16x16x32_bf16 v[28:31], v[242:245], v[210:213], v[28:31]
	v_mfma_f32_16x16x32_bf16 v[24:27], v[160:163], v[210:213], v[24:27]
	v_mfma_f32_16x16x32_bf16 v[20:23], v[242:245], v[218:221], v[20:23]
	v_mfma_f32_16x16x32_bf16 v[16:19], v[160:163], v[218:221], v[16:19]
	v_mfma_f32_16x16x32_bf16 v[12:15], v[242:245], v[226:229], v[12:15]
	v_mfma_f32_16x16x32_bf16 v[8:11], v[160:163], v[226:229], v[8:11]
	v_mfma_f32_16x16x32_bf16 v[4:7], v[242:245], v[234:237], v[4:7]
	v_mfma_f32_16x16x32_bf16 v[0:3], v[160:163], v[234:237], v[0:3]
	s_barrier
	ds_read_b128 v[160:163], v188
	ds_read_b128 v[190:193], v188 offset:1024
	ds_read_b128 v[194:197], v188 offset:2048
	ds_read_b128 v[198:201], v188 offset:3072
	s_add_u32 s30, s7, 0x100
	s_addc_u32 s31, s62, 0
	v_readfirstlane_b32 s7, v174
	v_lshl_add_u64 v[168:169], s[30:31], 0, v[128:129]
	s_mov_b32 m0, s7
	v_readfirstlane_b32 s7, v175
	ds_read_b128 v[202:205], v252 offset:32768
	ds_read_b128 v[206:209], v252 offset:33792
	ds_read_b128 v[210:213], v184 offset:32768
	ds_read_b128 v[214:217], v184 offset:33792
	ds_read_b128 v[218:221], v185 offset:32768
	ds_read_b128 v[222:225], v185 offset:33792
	ds_read_b128 v[226:229], v186 offset:32768
	ds_read_b128 v[230:233], v186 offset:33792
	global_load_lds_dwordx4 v[168:169], off
	v_lshl_add_u64 v[168:169], s[30:31], 0, v[130:131]
	s_mov_b32 m0, s7
	s_nop 0
	global_load_lds_dwordx4 v[168:169], off
	s_waitcnt lgkmcnt(8)
	s_barrier
	s_waitcnt lgkmcnt(0)
	s_waitcnt lgkmcnt(0)
	v_mfma_f32_16x16x32_bf16 v[100:103], v[160:163], v[202:205], v[100:103]
	v_mfma_f32_16x16x32_bf16 v[124:127], v[194:197], v[202:205], v[124:127]
	v_mfma_f32_16x16x32_bf16 v[120:123], v[160:163], v[210:213], v[120:123]
	v_mfma_f32_16x16x32_bf16 v[116:119], v[194:197], v[210:213], v[116:119]
	v_mfma_f32_16x16x32_bf16 v[112:115], v[160:163], v[218:221], v[112:115]
	v_mfma_f32_16x16x32_bf16 v[108:111], v[194:197], v[218:221], v[108:111]
	v_mfma_f32_16x16x32_bf16 v[104:107], v[160:163], v[226:229], v[104:107]
	v_mfma_f32_16x16x32_bf16 v[96:99], v[194:197], v[226:229], v[96:99]
	v_mfma_f32_16x16x32_bf16 v[100:103], v[190:193], v[206:209], v[100:103]
	v_mfma_f32_16x16x32_bf16 v[124:127], v[198:201], v[206:209], v[124:127]
	v_mfma_f32_16x16x32_bf16 v[120:123], v[190:193], v[214:217], v[120:123]
	v_mfma_f32_16x16x32_bf16 v[116:119], v[198:201], v[214:217], v[116:119]
	v_mfma_f32_16x16x32_bf16 v[112:115], v[190:193], v[222:225], v[112:115]
	v_mfma_f32_16x16x32_bf16 v[108:111], v[198:201], v[222:225], v[108:111]
	v_mfma_f32_16x16x32_bf16 v[104:107], v[190:193], v[230:233], v[104:107]
	v_mfma_f32_16x16x32_bf16 v[96:99], v[198:201], v[230:233], v[96:99]
	s_barrier
	s_add_u32 s30, s63, 0x180
	s_addc_u32 s31, s65, 0
	v_readfirstlane_b32 s7, v176
	v_lshl_add_u64 v[168:169], s[30:31], 0, v[132:133]
	s_mov_b32 m0, s7
	v_readfirstlane_b32 s7, v177
	ds_read_b128 v[234:237], v189
	ds_read_b128 v[238:241], v189 offset:1024
	ds_read_b128 v[242:245], v189 offset:2048
	ds_read_b128 v[246:249], v189 offset:3072
	global_load_lds_dwordx4 v[168:169], off
	v_lshl_add_u64 v[168:169], s[30:31], 0, v[136:137]
	s_mov_b32 m0, s7
	s_nop 0
	global_load_lds_dwordx4 v[168:169], off
	s_barrier
	s_waitcnt lgkmcnt(0)
	s_waitcnt lgkmcnt(0)
	v_mfma_f32_16x16x32_bf16 v[92:95], v[234:237], v[202:205], v[92:95]
	v_mfma_f32_16x16x32_bf16 v[88:91], v[242:245], v[202:205], v[88:91]
	v_mfma_f32_16x16x32_bf16 v[84:87], v[234:237], v[210:213], v[84:87]
	v_mfma_f32_16x16x32_bf16 v[80:83], v[242:245], v[210:213], v[80:83]
	v_mfma_f32_16x16x32_bf16 v[76:79], v[234:237], v[218:221], v[76:79]
	v_mfma_f32_16x16x32_bf16 v[72:75], v[242:245], v[218:221], v[72:75]
	v_mfma_f32_16x16x32_bf16 v[68:71], v[234:237], v[226:229], v[68:71]
	v_mfma_f32_16x16x32_bf16 v[64:67], v[242:245], v[226:229], v[64:67]
	v_mfma_f32_16x16x32_bf16 v[92:95], v[238:241], v[206:209], v[92:95]
	v_mfma_f32_16x16x32_bf16 v[88:91], v[246:249], v[206:209], v[88:91]
	v_mfma_f32_16x16x32_bf16 v[84:87], v[238:241], v[214:217], v[84:87]
	v_mfma_f32_16x16x32_bf16 v[80:83], v[246:249], v[214:217], v[80:83]
	v_mfma_f32_16x16x32_bf16 v[76:79], v[238:241], v[222:225], v[76:79]
	v_mfma_f32_16x16x32_bf16 v[72:75], v[246:249], v[222:225], v[72:75]
	v_mfma_f32_16x16x32_bf16 v[68:71], v[238:241], v[230:233], v[68:71]
	v_mfma_f32_16x16x32_bf16 v[64:67], v[246:249], v[230:233], v[64:67]
	s_add_u32 s30, s66, 0x180
	s_addc_u32 s31, s67, 0
	v_readfirstlane_b32 s7, v178
	v_lshl_add_u64 v[168:169], s[30:31], 0, v[128:129]
	s_mov_b32 m0, s7
	v_readfirstlane_b32 s7, v179
	s_barrier
; #define LDA(dst, b, h) _Pragma("unroll") for (int m = 0; m < 4; ++m) _Pragma("unroll") for (int k = 0; k < 2; ++k) \
;     dst[m][k] = *reinterpret_cast<const bf16x8*>((char*)SA(b, h) + lds_byte(wr * 64 + m * 16 + fr, k * 32 + fq * 8))
; #define LDB(dst, b, h) _Pragma("unroll") for (int n = 0; n < 2; ++n) _Pragma("unroll") for (int k = 0; k < 2; ++k) \
;     dst[n][k] = *reinterpret_cast<const bf16x8*>((char*)SB(b, h) + lds_byte(wc * 32 + n * 16 + fr, k * 32 + fq * 8))
; #define MMA(ai, bj, At_, Bt_) do { __builtin_amdgcn_s_setprio(1); \
;     _Pragma("unroll") for (int m = 0; m < 4; ++m) _Pragma("unroll") for (int n = 0; n < 2; ++n) _Pragma("unroll") for (int k = 0; k < 2; ++k) \
;       acc[ai][bj][m][n] = __builtin_amdgcn_mfma_f32_16x16x32_bf16(Bt_[n][k], At_[m][k], acc[ai][bj][m][n], 0, 0, 0); \
;     __builtin_amdgcn_s_setprio(0); } while (0)
; #define WAIT_V(n) asm volatile("s_waitcnt vmcnt(" #n ")" ::: "memory")
; #define WAIT_L(n) asm volatile("s_waitcnt lgkmcnt(" #n ")" ::: "memory")
; #define BAR __builtin_amdgcn_s_barrier()
; #define SCHED __builtin_amdgcn_sched_barrier(0)
; __device__ __forceinline__ void gemm_tile(const TileDesc& td, unsigned char* lds) {
;     ...
;         LDA(At, 1, 1); STAGE(SA(1, 0), A, lda, brow, t + 3);
;         BAR; WAIT_L(0); MMA(1, 0, At, B0); BAR; SCHED;
;         STAGE(SB(1, 1), Bt, ldb, bcol + HALF, t + 3);
;         WAIT_V(6); BAR; MMA(1, 1, At, B1); BAR;
;     }
;     { LDB(B0, 0, 0); LDA(At, 0, 0); STAGE(SA(1, 1), A, lda, brow + HALF, nt - 1);
;       BAR; WAIT_L(0); MMA(0, 0, At, B0); BAR;
	ds_read_b128 v[202:205], v252 offset:49152
	ds_read_b128 v[206:209], v252 offset:50176
	ds_read_b128 v[210:213], v184 offset:49152
	ds_read_b128 v[214:217], v184 offset:50176
	ds_read_b128 v[218:221], v185 offset:49152
	ds_read_b128 v[222:225], v185 offset:50176
	ds_read_b128 v[226:229], v186 offset:49152
	ds_read_b128 v[230:233], v186 offset:50176
	global_load_lds_dwordx4 v[168:169], off
	v_lshl_add_u64 v[168:169], s[30:31], 0, v[130:131]
	s_mov_b32 m0, s7
	s_nop 0
	global_load_lds_dwordx4 v[168:169], off
	s_barrier
	s_waitcnt lgkmcnt(0)
	s_waitcnt lgkmcnt(0)
	v_mfma_f32_16x16x32_bf16 v[60:63], v[160:163], v[202:205], v[60:63]
	v_mfma_f32_16x16x32_bf16 v[56:59], v[194:197], v[202:205], v[56:59]
	v_mfma_f32_16x16x32_bf16 v[52:55], v[160:163], v[210:213], v[52:55]
	v_mfma_f32_16x16x32_bf16 v[48:51], v[194:197], v[210:213], v[48:51]
	v_mfma_f32_16x16x32_bf16 v[44:47], v[160:163], v[218:221], v[44:47]
	v_mfma_f32_16x16x32_bf16 v[40:43], v[194:197], v[218:221], v[40:43]
	v_mfma_f32_16x16x32_bf16 v[36:39], v[160:163], v[226:229], v[36:39]
	v_mfma_f32_16x16x32_bf16 v[32:35], v[194:197], v[226:229], v[32:35]
	v_mfma_f32_16x16x32_bf16 v[60:63], v[190:193], v[206:209], v[60:63]
	v_mfma_f32_16x16x32_bf16 v[56:59], v[198:201], v[206:209], v[56:59]
	v_mfma_f32_16x16x32_bf16 v[52:55], v[190:193], v[214:217], v[52:55]
	v_mfma_f32_16x16x32_bf16 v[48:51], v[198:201], v[214:217], v[48:51]
	v_mfma_f32_16x16x32_bf16 v[44:47], v[190:193], v[222:225], v[44:47]
	v_mfma_f32_16x16x32_bf16 v[40:43], v[198:201], v[222:225], v[40:43]
	v_mfma_f32_16x16x32_bf16 v[36:39], v[190:193], v[230:233], v[36:39]
	v_mfma_f32_16x16x32_bf16 v[32:35], v[198:201], v[230:233], v[32:35]
	s_barrier
	s_add_u32 s30, s70, 0x180
	s_addc_u32 s31, s88, 0
	v_readfirstlane_b32 s7, v180
	v_lshl_add_u64 v[160:161], s[30:31], 0, v[132:133]
	s_mov_b32 m0, s7
	v_readfirstlane_b32 s7, v181
	global_load_lds_dwordx4 v[160:161], off
	v_lshl_add_u64 v[160:161], s[30:31], 0, v[136:137]
	s_mov_b32 m0, s7
	s_nop 0
	global_load_lds_dwordx4 v[160:161], off
	s_waitcnt vmcnt(6)
	s_barrier
	v_mfma_f32_16x16x32_bf16 v[28:31], v[234:237], v[202:205], v[28:31]
	v_mfma_f32_16x16x32_bf16 v[24:27], v[242:245], v[202:205], v[24:27]
	v_mfma_f32_16x16x32_bf16 v[20:23], v[234:237], v[210:213], v[20:23]
	v_mfma_f32_16x16x32_bf16 v[16:19], v[242:245], v[210:213], v[16:19]
	v_mfma_f32_16x16x32_bf16 v[12:15], v[234:237], v[218:221], v[12:15]
	v_mfma_f32_16x16x32_bf16 v[8:11], v[242:245], v[218:221], v[8:11]
	v_mfma_f32_16x16x32_bf16 v[4:7], v[234:237], v[226:229], v[4:7]
	v_mfma_f32_16x16x32_bf16 v[0:3], v[242:245], v[226:229], v[0:3]
	v_mfma_f32_16x16x32_bf16 v[28:31], v[238:241], v[206:209], v[28:31]
	v_mfma_f32_16x16x32_bf16 v[24:27], v[246:249], v[206:209], v[24:27]
	v_mfma_f32_16x16x32_bf16 v[20:23], v[238:241], v[214:217], v[20:23]
	v_mfma_f32_16x16x32_bf16 v[16:19], v[246:249], v[214:217], v[16:19]
	v_mfma_f32_16x16x32_bf16 v[12:15], v[238:241], v[222:225], v[12:15]
	v_mfma_f32_16x16x32_bf16 v[8:11], v[246:249], v[222:225], v[8:11]
	v_mfma_f32_16x16x32_bf16 v[4:7], v[238:241], v[230:233], v[4:7]
	v_mfma_f32_16x16x32_bf16 v[0:3], v[246:249], v[230:233], v[0:3]
	s_add_u32 s78, s78, 0x100
	s_addc_u32 s79, s79, 0
	s_cmp_lt_i32 s3, s2
	s_barrier
	s_cbranch_scc1 .LBB0_247
	v_or_b32_e32 v182, 0x400, v138
	v_or_b32_e32 v183, 0x800, v138
	v_or_b32_e32 v184, 0xc00, v138
	v_mov_b32_e32 v185, v154
	v_mov_b32_e32 v235, v159
	v_mov_b32_e32 v236, v172
	v_mov_b32_e32 v172, v170
	v_mov_b32_e32 v170, v173
	v_mov_b32_e32 v237, v165
	v_mov_b32_e32 v165, v167
	v_mov_b32_e32 v238, v135
	v_mov_b32_e32 v135, v171
	v_mov_b32_e32 v167, 0x42000000
.LBB0_249:
	v_add_u32_e32 v132, v151, v138
	v_add_u32_e32 v136, v151, v182
	ds_read_b128 v[152:155], v132
	ds_read_b128 v[160:163], v136
	v_add_u32_e32 v132, v151, v183
	v_add_u32_e32 v136, v151, v184
	s_ashr_i32 s7, s6, 31
	ds_read_b128 v[174:177], v132
	ds_read_b128 v[178:181], v136
	v_add_u32_e32 v136, 0, v142
	s_lshl_b64 s[2:3], s[6:7], 7
	v_add_u32_e32 v169, v136, v145
	v_add_u32_e32 v230, v136, v146
	v_add_u32_e32 v136, 0, v142
	s_add_u32 s2, s4, s2
	v_add_u32_e32 v231, v136, v147
	v_add_u32_e32 v232, v136, v148
	v_add_u32_e32 v136, 0, v142
	s_addc_u32 s3, s5, s3
	v_add_u32_e32 v233, v136, v149
	v_add_u32_e32 v234, v136, v150
	s_add_u32 s2, s2, 0xffffff80
	v_add_u32_e32 v136, 0xc000, v139
	v_add_u32_e32 v132, 0, v142
	s_addc_u32 s3, s3, -1
	v_readfirstlane_b32 s4, v136
	v_add_u32_e32 v168, v132, v185
	v_lshl_add_u64 v[128:129], s[2:3], 0, v[128:129]
	s_mov_b32 m0, s4
	v_add_u32_e32 v132, v132, v144
	ds_read_b128 v[186:189], v168
	ds_read_b128 v[190:193], v132
	ds_read_b128 v[194:197], v169
	ds_read_b128 v[198:201], v230
	ds_read_b128 v[144:147], v231
	ds_read_b128 v[202:205], v232
	ds_read_b128 v[148:151], v233
	ds_read_b128 v[206:209], v234
	global_load_lds_dwordx4 v[128:129], off
	v_lshl_add_u64 v[128:129], s[2:3], 0, v[130:131]
	v_add_u32_e32 v130, 0xe000, v139
	s_nop 0
	v_readfirstlane_b32 s2, v130
	s_mov_b32 m0, s2
	s_nop 0
	global_load_lds_dwordx4 v[128:129], off
	s_barrier
; #define LDA(dst, b, h) _Pragma("unroll") for (int m = 0; m < 4; ++m) _Pragma("unroll") for (int k = 0; k < 2; ++k) \
;     dst[m][k] = *reinterpret_cast<const bf16x8*>((char*)SA(b, h) + lds_byte(wr * 64 + m * 16 + fr, k * 32 + fq * 8))
; #define LDB(dst, b, h) _Pragma("unroll") for (int n = 0; n < 2; ++n) _Pragma("unroll") for (int k = 0; k < 2; ++k) \
;     dst[n][k] = *reinterpret_cast<const bf16x8*>((char*)SB(b, h) + lds_byte(wc * 32 + n * 16 + fr, k * 32 + fq * 8))
; #define MMA(ai, bj, At_, Bt_) do { __builtin_amdgcn_s_setprio(1); \
;     _Pragma("unroll") for (int m = 0; m < 4; ++m) _Pragma("unroll") for (int n = 0; n < 2; ++n) _Pragma("unroll") for (int k = 0; k < 2; ++k) \
;       acc[ai][bj][m][n] = __builtin_amdgcn_mfma_f32_16x16x32_bf16(Bt_[n][k], At_[m][k], acc[ai][bj][m][n], 0, 0, 0); \
;     __builtin_amdgcn_s_setprio(0); } while (0)
; #define WAIT_V(n) asm volatile("s_waitcnt vmcnt(" #n ")" ::: "memory")
; #define WAIT_L(n) asm volatile("s_waitcnt lgkmcnt(" #n ")" ::: "memory")
; #define BAR __builtin_amdgcn_s_barrier()
; __device__ __forceinline__ void gemm_tile(const TileDesc& td, unsigned char* lds) {
;     ...
;       BAR; WAIT_L(0); MMA(0, 0, At, B0); BAR;
;       LDB(B1, 0, 1); BAR; WAIT_L(0); MMA(0, 1, At, B1); BAR;
;       LDA(At, 0, 1); WAIT_V(4); BAR; WAIT_L(0); MMA(1, 0, At, B0); MMA(1, 1, At, B1); BAR; }
;     { LDB(B0, 1, 0); LDA(At, 1, 0); WAIT_V(2); BAR; WAIT_L(0); MMA(0, 0, At, B0); BAR;
	s_waitcnt lgkmcnt(0)
	s_waitcnt lgkmcnt(0)
	v_mfma_f32_16x16x32_bf16 v[100:103], v[152:155], v[186:189], v[100:103]
	v_mfma_f32_16x16x32_bf16 v[96:99], v[174:177], v[148:151], v[96:99]
	v_mfma_f32_16x16x32_bf16 v[100:103], v[160:163], v[190:193], v[100:103]
	v_mfma_f32_16x16x32_bf16 v[124:127], v[174:177], v[186:189], v[124:127]
	v_mfma_f32_16x16x32_bf16 v[120:123], v[152:155], v[194:197], v[120:123]
	v_mfma_f32_16x16x32_bf16 v[116:119], v[174:177], v[194:197], v[116:119]
	v_mfma_f32_16x16x32_bf16 v[112:115], v[152:155], v[144:147], v[112:115]
	v_mfma_f32_16x16x32_bf16 v[108:111], v[174:177], v[144:147], v[108:111]
	v_mfma_f32_16x16x32_bf16 v[104:107], v[152:155], v[148:151], v[104:107]
	v_mfma_f32_16x16x32_bf16 v[96:99], v[178:181], v[206:209], v[96:99]
	v_mfma_f32_16x16x32_bf16 v[128:131], v[178:181], v[190:193], v[124:127]
	v_mfma_f32_16x16x32_bf16 v[210:213], v[160:163], v[198:201], v[120:123]
	v_mfma_f32_16x16x32_bf16 v[214:217], v[178:181], v[198:201], v[116:119]
	v_mfma_f32_16x16x32_bf16 v[218:221], v[160:163], v[202:205], v[112:115]
	v_mfma_f32_16x16x32_bf16 v[222:225], v[178:181], v[202:205], v[108:111]
	v_mfma_f32_16x16x32_bf16 v[226:229], v[160:163], v[206:209], v[104:107]
	s_nop 1
	v_add_u32_e32 v104, v143, v138
	v_add_u32_e32 v108, v143, v182
	v_add_u32_e32 v112, v143, v183
	v_add_u32_e32 v116, v143, v184
	s_barrier
	ds_read_b128 v[104:107], v104
	ds_read_b128 v[108:111], v108
	ds_read_b128 v[112:115], v112
	ds_read_b128 v[116:119], v116
	s_barrier
	s_waitcnt lgkmcnt(0)
	s_waitcnt lgkmcnt(0)
	v_mfma_f32_16x16x32_bf16 v[92:95], v[104:107], v[186:189], v[92:95]
	v_mfma_f32_16x16x32_bf16 v[88:91], v[112:115], v[186:189], v[88:91]
	v_mfma_f32_16x16x32_bf16 v[84:87], v[104:107], v[194:197], v[84:87]
	v_mfma_f32_16x16x32_bf16 v[80:83], v[112:115], v[194:197], v[80:83]
	v_mfma_f32_16x16x32_bf16 v[76:79], v[104:107], v[144:147], v[76:79]
	v_mfma_f32_16x16x32_bf16 v[72:75], v[112:115], v[144:147], v[72:75]
	v_mfma_f32_16x16x32_bf16 v[68:71], v[104:107], v[148:151], v[68:71]
	v_mfma_f32_16x16x32_bf16 v[64:67], v[112:115], v[148:151], v[64:67]
	v_mfma_f32_16x16x32_bf16 v[92:95], v[108:111], v[190:193], v[92:95]
	v_mfma_f32_16x16x32_bf16 v[88:91], v[116:119], v[190:193], v[88:91]
	v_mfma_f32_16x16x32_bf16 v[84:87], v[108:111], v[198:201], v[84:87]
	v_mfma_f32_16x16x32_bf16 v[80:83], v[116:119], v[198:201], v[80:83]
	v_mfma_f32_16x16x32_bf16 v[76:79], v[108:111], v[202:205], v[76:79]
	v_mfma_f32_16x16x32_bf16 v[72:75], v[116:119], v[202:205], v[72:75]
	v_mfma_f32_16x16x32_bf16 v[68:71], v[108:111], v[206:209], v[68:71]
	v_mfma_f32_16x16x32_bf16 v[64:67], v[116:119], v[206:209], v[64:67]
	s_barrier
	ds_read_b128 v[120:123], v168 offset:16384
	ds_read_b128 v[124:127], v132 offset:16384
	ds_read_b128 v[142:145], v169 offset:16384
	ds_read_b128 v[146:149], v230 offset:16384
	ds_read_b128 v[186:189], v231 offset:16384
	ds_read_b128 v[190:193], v232 offset:16384
	ds_read_b128 v[194:197], v233 offset:16384
	ds_read_b128 v[198:201], v234 offset:16384
	s_waitcnt vmcnt(4)
	s_barrier
	s_waitcnt lgkmcnt(0)
	s_waitcnt lgkmcnt(0)
	v_mfma_f32_16x16x32_bf16 v[60:63], v[152:155], v[120:123], v[60:63]
	v_mfma_f32_16x16x32_bf16 v[56:59], v[174:177], v[120:123], v[56:59]
	v_mfma_f32_16x16x32_bf16 v[52:55], v[152:155], v[142:145], v[52:55]
	v_mfma_f32_16x16x32_bf16 v[48:51], v[174:177], v[142:145], v[48:51]
	v_mfma_f32_16x16x32_bf16 v[44:47], v[152:155], v[186:189], v[44:47]
	v_mfma_f32_16x16x32_bf16 v[40:43], v[174:177], v[186:189], v[40:43]
	v_mfma_f32_16x16x32_bf16 v[36:39], v[152:155], v[194:197], v[36:39]
	v_mfma_f32_16x16x32_bf16 v[32:35], v[174:177], v[194:197], v[32:35]
	v_mfma_f32_16x16x32_bf16 v[60:63], v[160:163], v[124:127], v[60:63]
	v_mfma_f32_16x16x32_bf16 v[56:59], v[178:181], v[124:127], v[56:59]
	v_mfma_f32_16x16x32_bf16 v[52:55], v[160:163], v[146:149], v[52:55]
	v_mfma_f32_16x16x32_bf16 v[48:51], v[178:181], v[146:149], v[48:51]
	v_mfma_f32_16x16x32_bf16 v[44:47], v[160:163], v[190:193], v[44:47]
	v_mfma_f32_16x16x32_bf16 v[40:43], v[178:181], v[190:193], v[40:43]
	v_mfma_f32_16x16x32_bf16 v[36:39], v[160:163], v[198:201], v[36:39]
	v_mfma_f32_16x16x32_bf16 v[32:35], v[178:181], v[198:201], v[32:35]
	v_mfma_f32_16x16x32_bf16 v[28:31], v[104:107], v[120:123], v[28:31]
	v_mfma_f32_16x16x32_bf16 v[24:27], v[112:115], v[120:123], v[24:27]
	v_mfma_f32_16x16x32_bf16 v[20:23], v[104:107], v[142:145], v[20:23]
	v_mfma_f32_16x16x32_bf16 v[16:19], v[112:115], v[142:145], v[16:19]
	v_mfma_f32_16x16x32_bf16 v[12:15], v[104:107], v[186:189], v[12:15]
	v_mfma_f32_16x16x32_bf16 v[8:11], v[112:115], v[186:189], v[8:11]
	v_mfma_f32_16x16x32_bf16 v[4:7], v[104:107], v[194:197], v[4:7]
	v_mfma_f32_16x16x32_bf16 v[0:3], v[112:115], v[194:197], v[0:3]
	v_mfma_f32_16x16x32_bf16 v[28:31], v[108:111], v[124:127], v[28:31]
	v_mfma_f32_16x16x32_bf16 v[24:27], v[116:119], v[124:127], v[24:27]
	v_mfma_f32_16x16x32_bf16 v[20:23], v[108:111], v[146:149], v[20:23]
	v_mfma_f32_16x16x32_bf16 v[16:19], v[116:119], v[146:149], v[16:19]
	v_mfma_f32_16x16x32_bf16 v[12:15], v[108:111], v[190:193], v[12:15]
	v_mfma_f32_16x16x32_bf16 v[8:11], v[116:119], v[190:193], v[8:11]
	v_mfma_f32_16x16x32_bf16 v[4:7], v[108:111], v[198:201], v[4:7]
	v_mfma_f32_16x16x32_bf16 v[0:3], v[116:119], v[198:201], v[0:3]
	v_add_u32_e32 v104, v141, v138
	s_barrier
	v_add_u32_e32 v105, v141, v182
	ds_read_b128 v[142:145], v104
	ds_read_b128 v[146:149], v105
	v_add_u32_e32 v104, v141, v183
	v_add_u32_e32 v105, v141, v184
	ds_read_b128 v[150:153], v104
	ds_read_b128 v[154:157], v105
	ds_read_b128 v[160:163], v168 offset:32768
	ds_read_b128 v[174:177], v132 offset:32768
	ds_read_b128 v[178:181], v169 offset:32768
	ds_read_b128 v[186:189], v230 offset:32768
	ds_read_b128 v[190:193], v231 offset:32768
	ds_read_b128 v[194:197], v232 offset:32768
	ds_read_b128 v[198:201], v233 offset:32768
	ds_read_b128 v[202:205], v234 offset:32768
	s_waitcnt vmcnt(2)
	s_barrier
; #define LDA(dst, b, h) _Pragma("unroll") for (int m = 0; m < 4; ++m) _Pragma("unroll") for (int k = 0; k < 2; ++k) \
;     dst[m][k] = *reinterpret_cast<const bf16x8*>((char*)SA(b, h) + lds_byte(wr * 64 + m * 16 + fr, k * 32 + fq * 8))
; #define LDB(dst, b, h) _Pragma("unroll") for (int n = 0; n < 2; ++n) _Pragma("unroll") for (int k = 0; k < 2; ++k) \
;     dst[n][k] = *reinterpret_cast<const bf16x8*>((char*)SB(b, h) + lds_byte(wc * 32 + n * 16 + fr, k * 32 + fq * 8))
; #define MMA(ai, bj, At_, Bt_) do { __builtin_amdgcn_s_setprio(1); \
;     _Pragma("unroll") for (int m = 0; m < 4; ++m) _Pragma("unroll") for (int n = 0; n < 2; ++n) _Pragma("unroll") for (int k = 0; k < 2; ++k) \
;       acc[ai][bj][m][n] = __builtin_amdgcn_mfma_f32_16x16x32_bf16(Bt_[n][k], At_[m][k], acc[ai][bj][m][n], 0, 0, 0); \
;     __builtin_amdgcn_s_setprio(0); } while (0)
; #define WAIT_V(n) asm volatile("s_waitcnt vmcnt(" #n ")" ::: "memory")
; #define WAIT_L(n) asm volatile("s_waitcnt lgkmcnt(" #n ")" ::: "memory")
; #define BAR __builtin_amdgcn_s_barrier()
; __device__ __forceinline__ void gemm_tile(const TileDesc& td, unsigned char* lds) {
;     ...
;     { LDB(B0, 1, 0); LDA(At, 1, 0); WAIT_V(2); BAR; WAIT_L(0); MMA(0, 0, At, B0); BAR;
;       LDB(B1, 1, 1); WAIT_V(0); BAR; WAIT_L(0); MMA(0, 1, At, B1); BAR;
;       LDA(At, 1, 1); BAR; WAIT_L(0); MMA(1, 0, At, B0); MMA(1, 1, At, B1); BAR; }
;     if (wr == 0) BAR;
	s_waitcnt lgkmcnt(0)
	s_waitcnt lgkmcnt(0)
	v_mfma_f32_16x16x32_bf16 v[100:103], v[142:145], v[160:163], v[100:103]
	v_mfma_f32_16x16x32_bf16 v[124:127], v[146:149], v[174:177], v[100:103]
	v_mfma_f32_16x16x32_bf16 v[100:103], v[150:153], v[160:163], v[128:131]
	v_mfma_f32_16x16x32_bf16 v[120:123], v[154:157], v[174:177], v[100:103]
	v_mfma_f32_16x16x32_bf16 v[100:103], v[142:145], v[178:181], v[210:213]
	v_mfma_f32_16x16x32_bf16 v[116:119], v[146:149], v[186:189], v[100:103]
	v_mfma_f32_16x16x32_bf16 v[100:103], v[150:153], v[178:181], v[214:217]
	v_mfma_f32_16x16x32_bf16 v[112:115], v[154:157], v[186:189], v[100:103]
	v_mfma_f32_16x16x32_bf16 v[100:103], v[142:145], v[190:193], v[218:221]
	v_mfma_f32_16x16x32_bf16 v[108:111], v[146:149], v[194:197], v[100:103]
	v_mfma_f32_16x16x32_bf16 v[100:103], v[150:153], v[190:193], v[222:225]
	v_mfma_f32_16x16x32_bf16 v[104:107], v[154:157], v[194:197], v[100:103]
	v_mfma_f32_16x16x32_bf16 v[100:103], v[142:145], v[198:201], v[226:229]
	v_mfma_f32_16x16x32_bf16 v[96:99], v[150:153], v[198:201], v[96:99]
	v_mfma_f32_16x16x32_bf16 v[100:103], v[146:149], v[202:205], v[100:103]
	v_mfma_f32_16x16x32_bf16 v[96:99], v[154:157], v[202:205], v[96:99]
	v_add_u32_e32 v128, v140, v138
	v_add_u32_e32 v136, v140, v182
	v_add_u32_e32 v141, v140, v183
	s_barrier
	ds_read_b128 v[128:131], v128
	ds_read_b128 v[136:139], v136
	v_add_u32_e32 v140, v140, v184
	ds_read_b128 v[182:185], v141
	ds_read_b128 v[206:209], v140
	s_waitcnt vmcnt(0)
	s_barrier
	s_waitcnt lgkmcnt(0)
	s_waitcnt lgkmcnt(0)
	v_mfma_f32_16x16x32_bf16 v[92:95], v[128:131], v[160:163], v[92:95]
	v_mfma_f32_16x16x32_bf16 v[88:91], v[182:185], v[160:163], v[88:91]
	v_mfma_f32_16x16x32_bf16 v[84:87], v[128:131], v[178:181], v[84:87]
	v_mfma_f32_16x16x32_bf16 v[80:83], v[182:185], v[178:181], v[80:83]
	v_mfma_f32_16x16x32_bf16 v[76:79], v[128:131], v[190:193], v[76:79]
	v_mfma_f32_16x16x32_bf16 v[72:75], v[182:185], v[190:193], v[72:75]
	v_mfma_f32_16x16x32_bf16 v[68:71], v[128:131], v[198:201], v[68:71]
	v_mfma_f32_16x16x32_bf16 v[64:67], v[182:185], v[198:201], v[64:67]
	v_mfma_f32_16x16x32_bf16 v[92:95], v[136:139], v[174:177], v[92:95]
	v_mfma_f32_16x16x32_bf16 v[88:91], v[206:209], v[174:177], v[88:91]
	v_mfma_f32_16x16x32_bf16 v[84:87], v[136:139], v[186:189], v[84:87]
	v_mfma_f32_16x16x32_bf16 v[80:83], v[206:209], v[186:189], v[80:83]
	v_mfma_f32_16x16x32_bf16 v[76:79], v[136:139], v[194:197], v[76:79]
	v_mfma_f32_16x16x32_bf16 v[72:75], v[206:209], v[194:197], v[72:75]
	v_mfma_f32_16x16x32_bf16 v[68:71], v[136:139], v[202:205], v[68:71]
	v_mfma_f32_16x16x32_bf16 v[64:67], v[206:209], v[202:205], v[64:67]
	s_barrier
	ds_read_b128 v[160:163], v168 offset:49152
	ds_read_b128 v[174:177], v132 offset:49152
	ds_read_b128 v[178:181], v169 offset:49152
	ds_read_b128 v[186:189], v230 offset:49152
	ds_read_b128 v[190:193], v231 offset:49152
	ds_read_b128 v[194:197], v232 offset:49152
	ds_read_b128 v[198:201], v233 offset:49152
	ds_read_b128 v[202:205], v234 offset:49152
	s_barrier
	s_waitcnt lgkmcnt(0)
	s_waitcnt lgkmcnt(0)
	v_mfma_f32_16x16x32_bf16 v[60:63], v[142:145], v[160:163], v[60:63]
	v_mfma_f32_16x16x32_bf16 v[56:59], v[150:153], v[160:163], v[56:59]
	v_mfma_f32_16x16x32_bf16 v[52:55], v[142:145], v[178:181], v[52:55]
	v_mfma_f32_16x16x32_bf16 v[48:51], v[150:153], v[178:181], v[48:51]
	v_mfma_f32_16x16x32_bf16 v[44:47], v[142:145], v[190:193], v[44:47]
	v_mfma_f32_16x16x32_bf16 v[40:43], v[150:153], v[190:193], v[40:43]
	v_mfma_f32_16x16x32_bf16 v[36:39], v[142:145], v[198:201], v[36:39]
	v_mfma_f32_16x16x32_bf16 v[32:35], v[150:153], v[198:201], v[32:35]
	v_mfma_f32_16x16x32_bf16 v[60:63], v[146:149], v[174:177], v[60:63]
	v_mfma_f32_16x16x32_bf16 v[56:59], v[154:157], v[174:177], v[56:59]
	v_mfma_f32_16x16x32_bf16 v[52:55], v[146:149], v[186:189], v[52:55]
	v_mfma_f32_16x16x32_bf16 v[48:51], v[154:157], v[186:189], v[48:51]
	v_mfma_f32_16x16x32_bf16 v[44:47], v[146:149], v[194:197], v[44:47]
	v_mfma_f32_16x16x32_bf16 v[40:43], v[154:157], v[194:197], v[40:43]
	v_mfma_f32_16x16x32_bf16 v[36:39], v[146:149], v[202:205], v[36:39]
	v_mfma_f32_16x16x32_bf16 v[32:35], v[154:157], v[202:205], v[32:35]
	v_mfma_f32_16x16x32_bf16 v[28:31], v[128:131], v[160:163], v[28:31]
	v_mfma_f32_16x16x32_bf16 v[24:27], v[182:185], v[160:163], v[24:27]
	v_mfma_f32_16x16x32_bf16 v[20:23], v[128:131], v[178:181], v[20:23]
	v_mfma_f32_16x16x32_bf16 v[16:19], v[182:185], v[178:181], v[16:19]
	v_mfma_f32_16x16x32_bf16 v[12:15], v[128:131], v[190:193], v[12:15]
	v_mfma_f32_16x16x32_bf16 v[8:11], v[182:185], v[190:193], v[8:11]
	v_mfma_f32_16x16x32_bf16 v[4:7], v[128:131], v[198:201], v[4:7]
	v_mfma_f32_16x16x32_bf16 v[0:3], v[182:185], v[198:201], v[0:3]
	v_mfma_f32_16x16x32_bf16 v[28:31], v[136:139], v[174:177], v[28:31]
	v_mfma_f32_16x16x32_bf16 v[24:27], v[206:209], v[174:177], v[24:27]
	v_mfma_f32_16x16x32_bf16 v[20:23], v[136:139], v[186:189], v[20:23]
	v_mfma_f32_16x16x32_bf16 v[16:19], v[206:209], v[186:189], v[16:19]
	v_mfma_f32_16x16x32_bf16 v[12:15], v[136:139], v[194:197], v[12:15]
	v_mfma_f32_16x16x32_bf16 v[8:11], v[206:209], v[194:197], v[8:11]
	v_mfma_f32_16x16x32_bf16 v[4:7], v[136:139], v[202:205], v[4:7]
	v_mfma_f32_16x16x32_bf16 v[0:3], v[206:209], v[202:205], v[0:3]
	s_movk_i32 s2, 0x100
	v_cmp_gt_u32_e32 vcc, s2, v134
	s_barrier
	s_and_saveexec_b64 s[4:5], vcc
	s_cbranch_execz .LBB0_251
	s_barrier

; __device__ __forceinline__ void grid_barrier(unsigned* ctr, unsigned target) {
;     asm volatile("s_waitcnt vmcnt(0)" ::: "memory");
;     __syncthreads();
;     if (threadIdx.x == 0) {
;         __threadfence();
;         asm volatile("s_waitcnt vmcnt(0)" ::: "memory");
;         __hip_atomic_fetch_add(ctr, 1u, __ATOMIC_RELAXED, __HIP_MEMORY_SCOPE_AGENT);
;         while (__hip_atomic_load(ctr, __ATOMIC_RELAXED, __HIP_MEMORY_SCOPE_AGENT) < target) __builtin_amdgcn_s_sleep(1);
;         __threadfence();
;         asm volatile("s_waitcnt vmcnt(0)" ::: "memory");
;     }
;     __syncthreads();
; }
.Lxb_top_done:
	buffer_inv sc1
	s_waitcnt vmcnt(0)
	s_branch .LBB0_735
.Lxb_follower:
	s_sleep 1
	global_load_dword v0, v133, s[12:13] offset:3584 sc1
	s_add_i32 s5, s5, 1
	s_waitcnt vmcnt(0)
	v_cmp_gt_u32_e32 vcc, s7, v0
	s_cbranch_vccz .Lxb_fol_done
	s_cmp_lt_u32 s5, 0x10000
	s_cbranch_scc1 .Lxb_follower
.Lxb_fol_done:
	buffer_inv sc1
	s_waitcnt vmcnt(0)
